# queue-first workgroups stop after their prompt item instead of pulling the (by then empty) mixer queue again
# speedup vs baseline: 1.0018x; 1.0018x over previous
; __device__ __forceinline__ void p_mixer(const Args& a, int l, LAS unsigned char* lds, int tid, int lane, int wave, int bid, int G) {
;     ...
;     const bool qfirst = ((bid >> 3) & 1) != 0;
;     bool prompt_done = false, queue_empty = false; int pulled = 0;
; #pragma unroll 1
;     for (;;) {
;         if (!prompt_done && (!qfirst || pulled >= 1 || queue_empty)) {
; #pragma unroll 1
;             for (int it = bid; it < N_AP; it += G) { asm volatile("" : "+v"(tid)); lane = tid & 63; attn_prompt_item(a, l, it, lds, tid, lane, wave); }
;             prompt_done = true; continue;
;         }
;         if (queue_empty) break;
;         if (threadIdx.x == 0) slot[0] = __hip_atomic_fetch_add(head, 1u, __ATOMIC_RELAXED, __HIP_MEMORY_SCOPE_AGENT);
;         __syncthreads();
;         const int q = (int)slot[0];
;         __syncthreads();
;         if (q >= N_AS + N_CV) { queue_empty = true; continue; }
.LBB0_440:
	s_mov_b64 s[66:67], -1
	v_mov_b32_e32 v130, v131
	s_cmp_lg_u32 s42, 0x100
	s_cbranch_scc1 .Lqx_skip
	v_readlane_b32 s0, v254, 10
	s_nop 3
	s_cmp_eq_u32 s0, 0
	s_cbranch_scc0 .Lqx_skip
	s_mov_b64 s[68:69], -1
.Lqx_skip:
.LBB0_441:
	s_and_b64 vcc, exec, s[66:67]
	s_mov_b64 s[0:1], -1
	s_cbranch_vccnz .LBB0_445
	s_cmp_gt_i32 s93, 0
	v_readlane_b32 s2, v254, 10
	s_cselect_b64 s[0:1], -1, 0
	v_readlane_b32 s3, v254, 11
	s_or_b64 s[0:1], s[2:3], s[0:1]
	s_or_b64 s[4:5], s[68:69], s[0:1]
	s_mov_b64 s[0:1], -1
	s_and_b64 vcc, exec, s[4:5]
	s_cbranch_vccz .LBB0_445
	v_readlane_b32 s0, v254, 12
	v_readlane_b32 s1, v254, 13
	s_andn2_b64 vcc, exec, s[0:1]
	v_mov_b32_e32 v131, v130
	s_mov_b32 s2, s71
	s_cbranch_vccz .LBB0_459
